# non-temporal stores for the streaming outputs of LN(mid), LN(post) and comb
# baseline (speedup 1.0000x reference)
.Lcb_top:
	s_mov_b64 s[38:39], 0x27600000
	v_lshl_add_u64 v[42:43], v[12:13], 0, s[38:39]
	v_mov_b64_e32 v[20:21], v[192:193]
	v_mov_b64_e32 v[22:23], v[194:195]
	v_mov_b64_e32 v[24:25], v[196:197]
	v_mov_b64_e32 v[26:27], v[198:199]
	v_mov_b64_e32 v[28:29], v[200:201]
	v_mov_b64_e32 v[30:31], v[202:203]
	v_mov_b64_e32 v[0:1], v[204:205]
	v_mov_b64_e32 v[2:3], v[206:207]
	v_mov_b64_e32 v[8:9], v[208:209]
	v_mov_b64_e32 v[10:11], v[210:211]
	v_mov_b64_e32 v[4:5], v[212:213]
	v_mov_b64_e32 v[6:7], v[214:215]
	v_mov_b64_e32 v[12:13], v[216:217]
	v_mov_b64_e32 v[14:15], v[218:219]
	v_mov_b64_e32 v[16:17], v[220:221]
	v_mov_b64_e32 v[18:19], v[222:223]
	v_readlane_b32 s38, v254, 47
	v_readlane_b32 s39, v254, 48
	s_add_u32 s46, s46, s38
	s_addc_u32 s47, s47, s39
	v_lshl_add_u64 v[230:231], v[38:39], 0, s[76:77]
	s_mov_b64 s[38:39], 0x4fffff
	v_cmp_lt_u64_e64 s[100:101], s[38:39], v[230:231]
	v_lshl_add_u64 v[224:225], s[46:47], 0, v[32:33]
	v_lshl_add_u64 v[226:227], s[46:47], 0, v[36:37]
	v_lshl_add_u64 v[228:229], v[230:231], 0, s[76:77]
	s_mov_b64 s[38:39], 0x500000
	v_cmp_gt_u64_e64 s[98:99], s[38:39], v[228:229]
	v_readlane_b32 s38, v254, 51
	s_nop 1
	v_add_u32_e32 v235, s38, v34
	s_mov_b64 vcc, exec
	s_andn2_b64 exec, exec, s[100:101]
	v_and_b32_e32 v234, 0x3f8, v235
	v_lshlrev_b32_e32 v234, 2, v234
	global_load_dwordx4 v[216:219], v234, s[48:49] offset:16
	global_load_dwordx4 v[220:223], v234, s[48:49]
	s_mov_b64 s[38:39], 0x2c600000
	v_lshl_add_u64 v[232:233], v[224:225], 0, s[38:39]
	global_load_dwordx4 v[192:195], v[232:233], off
	s_mov_b64 s[38:39], 0x22600000
	v_lshl_add_u64 v[232:233], v[224:225], 0, s[38:39]
	global_load_dwordx4 v[196:199], v[232:233], off
	s_mov_b64 s[38:39], 0x27600000
	v_lshl_add_u64 v[232:233], v[224:225], 0, s[38:39]
	global_load_dwordx4 v[200:203], v[232:233], off
	s_and_saveexec_b64 s[52:53], s[98:99]
	s_mov_b64 s[38:39], 0x2c600000
	v_lshl_add_u64 v[232:233], v[226:227], 0, s[38:39]
	global_load_dwordx4 v[204:207], v[232:233], off
	s_mov_b64 s[38:39], 0x22600000
	v_lshl_add_u64 v[232:233], v[226:227], 0, s[38:39]
	global_load_dwordx4 v[208:211], v[232:233], off
	s_mov_b64 s[38:39], 0x27600000
	v_lshl_add_u64 v[232:233], v[226:227], 0, s[38:39]
	global_load_dwordx4 v[212:215], v[232:233], off
	s_or_b64 exec, exec, s[52:53]
	s_mov_b64 exec, vcc
	v_lshlrev_b32_e32 v44, 16, v28
	v_and_b32_e32 v45, 0xffff0000, v28
	v_lshlrev_b32_e32 v46, 16, v20
	v_and_b32_e32 v47, 0xffff0000, v20
	v_pk_add_f32 v[44:45], v[44:45], v[46:47]
	v_lshlrev_b32_e32 v46, 16, v24
	v_and_b32_e32 v47, 0xffff0000, v24
	v_pk_fma_f32 v[44:45], v[16:17], v[46:47], v[44:45]
	s_nop 0
	v_mul_f32_e32 v20, 0x3d372713, v44
	v_mul_f32_e32 v20, v44, v20
	v_fma_f32 v20, v44, v20, v44
	v_mul_f32_e32 v20, 0x3f4c422a, v20
	v_mul_f32_e32 v20, -2.0, v20
	v_mul_f32_e32 v20, 0x3fb8aa3b, v20
	v_exp_f32_e32 v46, v20
	v_mul_f32_e32 v20, 0x3d372713, v45
	v_mul_f32_e32 v20, v45, v20
	v_fma_f32 v20, v45, v20, v45
	v_mul_f32_e32 v20, 0x3f4c422a, v20
	v_mul_f32_e32 v20, -2.0, v20
	v_mul_f32_e32 v20, 0x3fb8aa3b, v20
	v_exp_f32_e32 v47, v20
	s_nop 0
	v_pk_add_f32 v[46:47], v[46:47], 1.0 op_sel_hi:[1,0]
	s_nop 0
	v_div_scale_f32 v20, s[38:39], v47, v47, v45
	v_rcp_f32_e32 v24, v20
	s_nop 0
	v_fma_f32 v28, -v20, v24, 1.0
	v_fmac_f32_e32 v24, v28, v24
	v_div_scale_f32 v28, vcc, v45, v47, v45
	v_mul_f32_e32 v48, v28, v24
	v_fma_f32 v49, -v20, v48, v28
	v_fmac_f32_e32 v48, v49, v24
	v_fma_f32 v20, -v20, v48, v28
	v_div_fmas_f32 v20, v20, v24, v48
	v_div_scale_f32 v24, s[38:39], v46, v46, v44
	v_rcp_f32_e32 v28, v24
	v_div_fixup_f32 v20, v20, v47, v45
	v_fma_f32 v45, -v24, v28, 1.0
	v_fmac_f32_e32 v28, v45, v28
	v_div_scale_f32 v45, vcc, v44, v46, v44
	v_mul_f32_e32 v47, v45, v28
	v_fma_f32 v48, -v24, v47, v45
	v_fmac_f32_e32 v47, v48, v28
	v_fma_f32 v24, -v24, v47, v45
	v_div_fmas_f32 v24, v24, v28, v47
	v_div_fixup_f32 v24, v24, v46, v44
	v_lshlrev_b32_e32 v28, 16, v29
	v_and_b32_e32 v29, 0xffff0000, v29
	v_lshlrev_b32_e32 v44, 16, v21
	v_and_b32_e32 v45, 0xffff0000, v21
	v_cvt_pk_bf16_f32 v20, v24, v20
	v_pk_add_f32 v[28:29], v[28:29], v[44:45]
	v_lshlrev_b32_e32 v24, 16, v25
	v_and_b32_e32 v25, 0xffff0000, v25
	v_pk_fma_f32 v[24:25], v[18:19], v[24:25], v[28:29]
	s_nop 0
	v_mul_f32_e32 v21, 0x3d372713, v24
	v_mul_f32_e32 v21, v24, v21
	v_fma_f32 v21, v24, v21, v24
	v_mul_f32_e32 v21, 0x3f4c422a, v21
	v_mul_f32_e32 v21, -2.0, v21
	v_mul_f32_e32 v21, 0x3fb8aa3b, v21
	v_exp_f32_e32 v28, v21
	v_mul_f32_e32 v21, 0x3d372713, v25
	v_mul_f32_e32 v21, v25, v21
	v_fma_f32 v21, v25, v21, v25
	v_mul_f32_e32 v21, 0x3f4c422a, v21
	v_mul_f32_e32 v21, -2.0, v21
	v_mul_f32_e32 v21, 0x3fb8aa3b, v21
	v_exp_f32_e32 v29, v21
	s_nop 0
	v_pk_add_f32 v[28:29], v[28:29], 1.0 op_sel_hi:[1,0]
	s_nop 0
	v_div_scale_f32 v21, s[38:39], v29, v29, v25
	v_rcp_f32_e32 v44, v21
	s_nop 0
	v_fma_f32 v45, -v21, v44, 1.0
	v_fmac_f32_e32 v44, v45, v44
	v_div_scale_f32 v45, vcc, v25, v29, v25
	v_mul_f32_e32 v46, v45, v44
	v_fma_f32 v47, -v21, v46, v45
	v_fmac_f32_e32 v46, v47, v44
	v_fma_f32 v21, -v21, v46, v45
	v_div_fmas_f32 v21, v21, v44, v46
	v_div_fixup_f32 v21, v21, v29, v25
	v_div_scale_f32 v25, s[38:39], v28, v28, v24
	v_rcp_f32_e32 v29, v25
	s_nop 0
	v_fma_f32 v44, -v25, v29, 1.0
	v_fmac_f32_e32 v29, v44, v29
	v_div_scale_f32 v44, vcc, v24, v28, v24
	v_mul_f32_e32 v45, v44, v29
	v_fma_f32 v46, -v25, v45, v44
	v_fmac_f32_e32 v45, v46, v29
	v_fma_f32 v25, -v25, v45, v44
	v_div_fmas_f32 v25, v25, v29, v45
	v_div_fixup_f32 v24, v25, v28, v24
	v_cvt_pk_bf16_f32 v21, v24, v21
	v_lshlrev_b32_e32 v24, 16, v30
	v_and_b32_e32 v25, 0xffff0000, v30
	v_lshlrev_b32_e32 v28, 16, v22
	v_and_b32_e32 v29, 0xffff0000, v22
	v_pk_add_f32 v[24:25], v[24:25], v[28:29]
	v_lshlrev_b32_e32 v28, 16, v26
	v_and_b32_e32 v29, 0xffff0000, v26
	v_pk_fma_f32 v[24:25], v[12:13], v[28:29], v[24:25]
	s_nop 0
	v_mul_f32_e32 v22, 0x3d372713, v24
	v_mul_f32_e32 v22, v24, v22
	v_fma_f32 v22, v24, v22, v24
	v_mul_f32_e32 v22, 0x3f4c422a, v22
	v_mul_f32_e32 v22, -2.0, v22
	v_mul_f32_e32 v22, 0x3fb8aa3b, v22
	v_exp_f32_e32 v28, v22
	v_mul_f32_e32 v22, 0x3d372713, v25
	v_mul_f32_e32 v22, v25, v22
	v_fma_f32 v22, v25, v22, v25
	v_mul_f32_e32 v22, 0x3f4c422a, v22
	v_mul_f32_e32 v22, -2.0, v22
	v_mul_f32_e32 v22, 0x3fb8aa3b, v22
	v_exp_f32_e32 v29, v22
	s_nop 0
	v_pk_add_f32 v[28:29], v[28:29], 1.0 op_sel_hi:[1,0]
	s_nop 0
	v_div_scale_f32 v22, s[38:39], v29, v29, v25
	v_rcp_f32_e32 v26, v22
	s_nop 0
	v_fma_f32 v30, -v22, v26, 1.0
	v_fmac_f32_e32 v26, v30, v26
	v_div_scale_f32 v30, vcc, v25, v29, v25
	v_mul_f32_e32 v44, v30, v26
	v_fma_f32 v45, -v22, v44, v30
	v_fmac_f32_e32 v44, v45, v26
	v_fma_f32 v22, -v22, v44, v30
	v_div_fmas_f32 v22, v22, v26, v44
	v_div_fixup_f32 v22, v22, v29, v25
	v_div_scale_f32 v25, s[38:39], v28, v28, v24
	v_rcp_f32_e32 v26, v25
	s_nop 0
	v_fma_f32 v29, -v25, v26, 1.0
	v_fmac_f32_e32 v26, v29, v26
	v_div_scale_f32 v29, vcc, v24, v28, v24
	v_mul_f32_e32 v30, v29, v26
	v_fma_f32 v44, -v25, v30, v29
	v_fmac_f32_e32 v30, v44, v26
	v_fma_f32 v25, -v25, v30, v29
	v_div_fmas_f32 v25, v25, v26, v30
	v_div_fixup_f32 v24, v25, v28, v24
	v_cvt_pk_bf16_f32 v22, v24, v22
	v_lshlrev_b32_e32 v24, 16, v31
	v_and_b32_e32 v25, 0xffff0000, v31
	v_lshlrev_b32_e32 v28, 16, v23
	v_and_b32_e32 v29, 0xffff0000, v23
	v_pk_add_f32 v[24:25], v[24:25], v[28:29]
	v_lshlrev_b32_e32 v26, 16, v27
	v_and_b32_e32 v27, 0xffff0000, v27
	v_pk_fma_f32 v[24:25], v[14:15], v[26:27], v[24:25]
	s_nop 0
	v_mul_f32_e32 v23, 0x3d372713, v24
	v_mul_f32_e32 v23, v24, v23
	v_fma_f32 v23, v24, v23, v24
	v_mul_f32_e32 v23, 0x3f4c422a, v23
	v_mul_f32_e32 v23, -2.0, v23
	v_mul_f32_e32 v23, 0x3fb8aa3b, v23
	v_exp_f32_e32 v26, v23
	v_mul_f32_e32 v23, 0x3d372713, v25
	v_mul_f32_e32 v23, v25, v23
	v_fma_f32 v23, v25, v23, v25
	v_mul_f32_e32 v23, 0x3f4c422a, v23
	v_mul_f32_e32 v23, -2.0, v23
	v_mul_f32_e32 v23, 0x3fb8aa3b, v23
	v_exp_f32_e32 v27, v23
	s_nop 0
	v_pk_add_f32 v[26:27], v[26:27], 1.0 op_sel_hi:[1,0]
	s_nop 0
	v_div_scale_f32 v23, s[38:39], v27, v27, v25
	v_rcp_f32_e32 v28, v23
	s_nop 0
	v_fma_f32 v29, -v23, v28, 1.0
	v_fmac_f32_e32 v28, v29, v28
	v_div_scale_f32 v29, vcc, v25, v27, v25
	v_mul_f32_e32 v30, v29, v28
	v_fma_f32 v31, -v23, v30, v29
	v_fmac_f32_e32 v30, v31, v28
	v_fma_f32 v23, -v23, v30, v29
	v_div_fmas_f32 v23, v23, v28, v30
	v_div_fixup_f32 v23, v23, v27, v25
	v_div_scale_f32 v25, s[38:39], v26, v26, v24
	v_rcp_f32_e32 v27, v25
	s_nop 0
	v_fma_f32 v28, -v25, v27, 1.0
	v_fmac_f32_e32 v27, v28, v27
	v_div_scale_f32 v28, vcc, v24, v26, v24
	v_mul_f32_e32 v29, v28, v27
	v_fma_f32 v30, -v25, v29, v28
	v_fmac_f32_e32 v29, v30, v27
	v_fma_f32 v25, -v25, v29, v28
	v_div_fmas_f32 v25, v25, v27, v29
	v_div_fixup_f32 v24, v25, v26, v24
	v_cvt_pk_bf16_f32 v23, v24, v23
	global_store_dwordx4 v[42:43], v[20:23], off nt
	s_and_saveexec_b64 s[52:53], s[42:43]
	s_cbranch_execz .LBB0_709
	v_lshlrev_b32_e32 v20, 16, v4
	v_and_b32_e32 v21, 0xffff0000, v4
	v_lshlrev_b32_e32 v22, 16, v0
	v_and_b32_e32 v23, 0xffff0000, v0
	v_pk_add_f32 v[20:21], v[22:23], v[20:21]
	v_lshlrev_b32_e32 v22, 16, v8
	v_and_b32_e32 v23, 0xffff0000, v8
	v_pk_fma_f32 v[16:17], v[16:17], v[22:23], v[20:21]
	s_nop 0
	v_mul_f32_e32 v0, 0x3d372713, v16
	v_mul_f32_e32 v0, v16, v0
	v_fma_f32 v0, v16, v0, v16
	v_mul_f32_e32 v0, 0x3f4c422a, v0
	v_mul_f32_e32 v0, -2.0, v0
	v_mul_f32_e32 v0, 0x3fb8aa3b, v0
	v_exp_f32_e32 v20, v0
	v_mul_f32_e32 v0, 0x3d372713, v17
	v_mul_f32_e32 v0, v17, v0
	v_fma_f32 v0, v17, v0, v17
	v_mul_f32_e32 v0, 0x3f4c422a, v0
	v_mul_f32_e32 v0, -2.0, v0
	v_mul_f32_e32 v0, 0x3fb8aa3b, v0
	v_exp_f32_e32 v21, v0
	s_nop 0
	v_pk_add_f32 v[20:21], v[20:21], 1.0 op_sel_hi:[1,0]
	s_nop 0
	v_div_scale_f32 v0, s[38:39], v21, v21, v17
	v_rcp_f32_e32 v4, v0
	s_nop 0
	v_fma_f32 v8, -v0, v4, 1.0
	v_fmac_f32_e32 v4, v8, v4
	v_div_scale_f32 v8, vcc, v17, v21, v17
	v_mul_f32_e32 v22, v8, v4
	v_fma_f32 v23, -v0, v22, v8
	v_fmac_f32_e32 v22, v23, v4
	v_fma_f32 v0, -v0, v22, v8
	v_div_fmas_f32 v0, v0, v4, v22
	v_div_scale_f32 v4, s[38:39], v20, v20, v16
	v_rcp_f32_e32 v8, v4
	v_div_fixup_f32 v0, v0, v21, v17
	v_fma_f32 v17, -v4, v8, 1.0
	v_fmac_f32_e32 v8, v17, v8
	v_div_scale_f32 v17, vcc, v16, v20, v16
	v_mul_f32_e32 v21, v17, v8
	v_fma_f32 v22, -v4, v21, v17
	v_fmac_f32_e32 v21, v22, v8
	v_fma_f32 v4, -v4, v21, v17
	v_div_fmas_f32 v4, v4, v8, v21
	v_div_fixup_f32 v4, v4, v20, v16
	v_cvt_pk_bf16_f32 v0, v4, v0
	v_lshlrev_b32_e32 v4, 16, v5
	v_and_b32_e32 v5, 0xffff0000, v5
	v_lshlrev_b32_e32 v16, 16, v1
	v_and_b32_e32 v17, 0xffff0000, v1
	v_pk_add_f32 v[4:5], v[16:17], v[4:5]
	v_lshlrev_b32_e32 v8, 16, v9
	v_and_b32_e32 v9, 0xffff0000, v9
	v_pk_fma_f32 v[4:5], v[18:19], v[8:9], v[4:5]
	s_nop 0
	v_mul_f32_e32 v1, 0x3d372713, v4
	v_mul_f32_e32 v1, v4, v1
	v_fma_f32 v1, v4, v1, v4
	v_mul_f32_e32 v1, 0x3f4c422a, v1
	v_mul_f32_e32 v1, -2.0, v1
	v_mul_f32_e32 v1, 0x3fb8aa3b, v1
	v_exp_f32_e32 v8, v1
	v_mul_f32_e32 v1, 0x3d372713, v5
	v_mul_f32_e32 v1, v5, v1
	v_fma_f32 v1, v5, v1, v5
	v_mul_f32_e32 v1, 0x3f4c422a, v1
	v_mul_f32_e32 v1, -2.0, v1
	v_mul_f32_e32 v1, 0x3fb8aa3b, v1
	v_exp_f32_e32 v9, v1
	s_nop 0
	v_pk_add_f32 v[8:9], v[8:9], 1.0 op_sel_hi:[1,0]
	s_nop 0
	v_div_scale_f32 v1, s[38:39], v9, v9, v5
	v_rcp_f32_e32 v16, v1
	s_nop 0
	v_fma_f32 v17, -v1, v16, 1.0
	v_fmac_f32_e32 v16, v17, v16
	v_div_scale_f32 v17, vcc, v5, v9, v5
	v_mul_f32_e32 v18, v17, v16
	v_fma_f32 v19, -v1, v18, v17
	v_fmac_f32_e32 v18, v19, v16
	v_fma_f32 v1, -v1, v18, v17
	v_div_fmas_f32 v1, v1, v16, v18
	v_div_fixup_f32 v1, v1, v9, v5
	v_div_scale_f32 v5, s[38:39], v8, v8, v4
	v_rcp_f32_e32 v9, v5
	s_nop 0
	v_fma_f32 v16, -v5, v9, 1.0
	v_fmac_f32_e32 v9, v16, v9
	v_div_scale_f32 v16, vcc, v4, v8, v4
	v_mul_f32_e32 v17, v16, v9
	v_fma_f32 v18, -v5, v17, v16
	v_fmac_f32_e32 v17, v18, v9
	v_fma_f32 v5, -v5, v17, v16
	v_div_fmas_f32 v5, v5, v9, v17
	v_div_fixup_f32 v4, v5, v8, v4
	v_cvt_pk_bf16_f32 v1, v4, v1
	v_lshlrev_b32_e32 v4, 16, v6
	v_and_b32_e32 v5, 0xffff0000, v6
	v_lshlrev_b32_e32 v8, 16, v2
	v_and_b32_e32 v9, 0xffff0000, v2
	v_pk_add_f32 v[4:5], v[8:9], v[4:5]
	v_lshlrev_b32_e32 v8, 16, v10
	v_and_b32_e32 v9, 0xffff0000, v10
	v_pk_fma_f32 v[4:5], v[12:13], v[8:9], v[4:5]
	s_nop 0
	v_mul_f32_e32 v2, 0x3d372713, v4
	v_mul_f32_e32 v2, v4, v2
	v_fma_f32 v2, v4, v2, v4
	v_mul_f32_e32 v2, 0x3f4c422a, v2
	v_mul_f32_e32 v2, -2.0, v2
	v_mul_f32_e32 v2, 0x3fb8aa3b, v2
	v_exp_f32_e32 v8, v2
	v_mul_f32_e32 v2, 0x3d372713, v5
	v_mul_f32_e32 v2, v5, v2
	v_fma_f32 v2, v5, v2, v5
	v_mul_f32_e32 v2, 0x3f4c422a, v2
	v_mul_f32_e32 v2, -2.0, v2
	v_mul_f32_e32 v2, 0x3fb8aa3b, v2
	v_exp_f32_e32 v9, v2
	s_nop 0
	v_pk_add_f32 v[8:9], v[8:9], 1.0 op_sel_hi:[1,0]
	s_nop 0
	v_div_scale_f32 v2, s[38:39], v9, v9, v5
	v_rcp_f32_e32 v6, v2
	s_nop 0
	v_fma_f32 v10, -v2, v6, 1.0
	v_fmac_f32_e32 v6, v10, v6
	v_div_scale_f32 v10, vcc, v5, v9, v5
	v_mul_f32_e32 v12, v10, v6
	v_fma_f32 v13, -v2, v12, v10
	v_fmac_f32_e32 v12, v13, v6
	v_fma_f32 v2, -v2, v12, v10
	v_div_fmas_f32 v2, v2, v6, v12
	v_div_fixup_f32 v2, v2, v9, v5
	v_div_scale_f32 v5, s[38:39], v8, v8, v4
	v_rcp_f32_e32 v6, v5
	s_nop 0
	v_fma_f32 v9, -v5, v6, 1.0
	v_fmac_f32_e32 v6, v9, v6
	v_div_scale_f32 v9, vcc, v4, v8, v4
	v_mul_f32_e32 v10, v9, v6
	v_fma_f32 v12, -v5, v10, v9
	v_fmac_f32_e32 v10, v12, v6
	v_fma_f32 v5, -v5, v10, v9
	v_div_fmas_f32 v5, v5, v6, v10
	v_div_fixup_f32 v4, v5, v8, v4
	v_cvt_pk_bf16_f32 v2, v4, v2
	v_lshlrev_b32_e32 v4, 16, v7
	v_and_b32_e32 v5, 0xffff0000, v7
	v_lshlrev_b32_e32 v6, 16, v3
	v_and_b32_e32 v7, 0xffff0000, v3
	v_pk_add_f32 v[4:5], v[6:7], v[4:5]
	v_lshlrev_b32_e32 v6, 16, v11
	v_and_b32_e32 v7, 0xffff0000, v11
	v_pk_fma_f32 v[4:5], v[14:15], v[6:7], v[4:5]
	s_nop 0
	v_mul_f32_e32 v3, 0x3d372713, v4
	v_mul_f32_e32 v3, v4, v3
	v_fma_f32 v3, v4, v3, v4
	v_mul_f32_e32 v3, 0x3f4c422a, v3
	v_mul_f32_e32 v3, -2.0, v3
	v_mul_f32_e32 v3, 0x3fb8aa3b, v3
	v_exp_f32_e32 v6, v3
	v_mul_f32_e32 v3, 0x3d372713, v5
	v_mul_f32_e32 v3, v5, v3
	v_fma_f32 v3, v5, v3, v5
	v_mul_f32_e32 v3, 0x3f4c422a, v3
	v_mul_f32_e32 v3, -2.0, v3
	v_mul_f32_e32 v3, 0x3fb8aa3b, v3
	v_exp_f32_e32 v7, v3
	s_nop 0
	v_pk_add_f32 v[6:7], v[6:7], 1.0 op_sel_hi:[1,0]
	s_nop 0
	v_div_scale_f32 v3, s[38:39], v7, v7, v5
	v_rcp_f32_e32 v8, v3
	s_nop 0
	v_fma_f32 v9, -v3, v8, 1.0
	v_fmac_f32_e32 v8, v9, v8
	v_div_scale_f32 v9, vcc, v5, v7, v5
	v_mul_f32_e32 v10, v9, v8
	v_fma_f32 v11, -v3, v10, v9
	v_fmac_f32_e32 v10, v11, v8
	v_fma_f32 v3, -v3, v10, v9
	v_div_fmas_f32 v3, v3, v8, v10
	v_div_fixup_f32 v3, v3, v7, v5
	v_div_scale_f32 v5, s[38:39], v6, v6, v4
	v_rcp_f32_e32 v7, v5
	s_nop 0
	v_fma_f32 v8, -v5, v7, 1.0
	v_fmac_f32_e32 v7, v8, v7
	v_div_scale_f32 v8, vcc, v4, v6, v4
	v_mul_f32_e32 v9, v8, v7
	v_fma_f32 v10, -v5, v9, v8
	v_fmac_f32_e32 v9, v10, v7
	v_fma_f32 v5, -v5, v9, v8
	v_div_fmas_f32 v5, v5, v7, v9
	v_div_fixup_f32 v4, v5, v6, v4
	v_cvt_pk_bf16_f32 v3, v4, v3
	v_add_co_u32_e32 v4, vcc, 0x27600000, v40
	s_nop 1
	v_addc_co_u32_e32 v5, vcc, 0, v41, vcc
	global_store_dwordx4 v[4:5], v[0:3], off nt
	s_branch .LBB0_709

.LBB0_930:
	s_or_b64 exec, exec, s[52:53]
	v_lshlrev_b32_e32 v54, 16, v32
	v_and_b32_e32 v55, 0xffff0000, v32
	v_add_f32_e32 v11, 0, v54
	v_lshlrev_b32_e32 v32, 16, v33
	v_add_f32_e32 v11, v11, v55
	v_and_b32_e32 v33, 0xffff0000, v33
	v_add_f32_e32 v11, v11, v32
	v_lshlrev_b32_e32 v56, 16, v30
	v_add_f32_e32 v11, v11, v33
	v_and_b32_e32 v57, 0xffff0000, v30
	v_add_f32_e32 v11, v11, v56
	v_lshlrev_b32_e32 v30, 16, v31
	v_add_f32_e32 v11, v11, v57
	v_and_b32_e32 v31, 0xffff0000, v31
	v_add_f32_e32 v11, v11, v30
	v_lshlrev_b32_e32 v58, 16, v28
	v_add_f32_e32 v11, v11, v31
	v_and_b32_e32 v59, 0xffff0000, v28
	v_add_f32_e32 v11, v11, v58
	v_lshlrev_b32_e32 v60, 16, v29
	v_add_f32_e32 v11, v11, v59
	v_and_b32_e32 v61, 0xffff0000, v29
	v_add_f32_e32 v11, v11, v60
	v_lshlrev_b32_e32 v62, 16, v26
	v_add_f32_e32 v11, v11, v61
	v_and_b32_e32 v63, 0xffff0000, v26
	v_add_f32_e32 v11, v11, v62
	v_lshlrev_b32_e32 v64, 16, v27
	v_add_f32_e32 v11, v11, v63
	v_and_b32_e32 v65, 0xffff0000, v27
	v_add_f32_e32 v11, v11, v64
	v_add_f32_e32 v11, v11, v65
	v_cmp_lt_i32_e32 vcc, s22, v24
	s_and_b64 s[38:39], exec, s[44:45]
	s_or_b64 s[50:51], s[38:39], s[50:51]
	s_waitcnt lgkmcnt(0)
	v_lshl_add_u64 v[78:79], v[0:1], 0, v[6:7]
	s_mov_b32 s3, 0x1d600000
	v_mov_b32_e32 v15, v129
	v_lshl_add_u64 v[8:9], v[8:9], 0, s[4:5]
	v_lshl_add_u64 v[0:1], v[0:1], 0, s[4:5]
	s_nop 1
	v_add_f32_dpp v11, v11, v11 quad_perm:[1,0,3,2] row_mask:0xf bank_mask:0xf
	s_nop 1
	v_add_f32_dpp v11, v11, v11 quad_perm:[2,3,0,1] row_mask:0xf bank_mask:0xf
	s_nop 1
	v_add_f32_dpp v11, v11, v11 row_half_mirror row_mask:0xf bank_mask:0xf
	s_nop 1
	v_add_f32_dpp v11, v11, v11 row_mirror row_mask:0xf bank_mask:0xf
	s_nop 1
	v_mov_b32_e32 v13, v11
	v_mov_b32_e32 v250, v11
	s_nop 1
	v_permlane16_swap_b32 v13, v250
	s_nop 1
	v_add_f32_e32 v11, v13, v250
	v_mov_b32_e32 v13, v11
	v_mov_b32_e32 v250, v11
	s_nop 1
	v_permlane32_swap_b32 v13, v250
	s_nop 1
	v_add_f32_e32 v11, v13, v250
	v_mul_f32_e32 v66, 0x3a800000, v11
	v_add_u32_e32 v11, 0xffffe000, v24
	v_lshrrev_b32_e32 v11, 12, v11
	v_add_u32_e32 v11, 1, v11
	v_cndmask_b32_e32 v11, 0, v11, vcc
	v_mov_b64_e32 v[24:25], s[48:49]
	v_mad_u64_u32 v[24:25], s[38:39], v11, s23, v[24:25]
	s_mov_b64 s[38:39], 0x1000
	s_nop 0
	v_lshl_add_u64 v[68:69], v[24:25], 0, s[38:39]
	v_lshl_add_u64 v[24:25], v[24:25], 0, v[128:129]
	v_lshl_add_u64 v[26:27], v[68:69], 0, v[128:129]
	v_pk_add_f32 v[54:55], v[54:55], v[66:67] op_sel_hi:[1,0] neg_lo:[0,1] neg_hi:[0,1]
	v_pk_add_f32 v[32:33], v[32:33], v[66:67] op_sel_hi:[1,0] neg_lo:[0,1] neg_hi:[0,1]
	v_pk_mul_f32 v[72:73], v[54:55], v[54:55]
	v_mov_b32_e32 v11, v129
	v_pk_mul_f32 v[70:71], v[32:33], v[32:33]
	v_lshl_add_u64 v[80:81], v[68:69], 0, v[10:11]
	v_add_f32_e32 v11, v72, v73
	v_pk_add_f32 v[56:57], v[56:57], v[66:67] op_sel_hi:[1,0] neg_lo:[0,1] neg_hi:[0,1]
	v_add_f32_e32 v11, v70, v11
	v_pk_mul_f32 v[86:87], v[56:57], v[56:57]
	v_add_f32_e32 v11, v71, v11
	v_pk_add_f32 v[82:83], v[30:31], v[66:67] op_sel_hi:[1,0] neg_lo:[0,1] neg_hi:[0,1]
	v_add_f32_e32 v11, v86, v11
	v_pk_mul_f32 v[84:85], v[82:83], v[82:83]
	v_add_f32_e32 v11, v87, v11
	v_pk_add_f32 v[58:59], v[58:59], v[66:67] op_sel_hi:[1,0] neg_lo:[0,1] neg_hi:[0,1]
	v_add_f32_e32 v11, v84, v11
	v_pk_mul_f32 v[92:93], v[58:59], v[58:59]
	v_add_f32_e32 v11, v85, v11
	v_pk_add_f32 v[60:61], v[60:61], v[66:67] op_sel_hi:[1,0] neg_lo:[0,1] neg_hi:[0,1]
	v_add_f32_e32 v11, v92, v11
	v_pk_mul_f32 v[90:91], v[60:61], v[60:61]
	v_add_f32_e32 v11, v93, v11
	v_pk_add_f32 v[30:31], v[62:63], v[66:67] op_sel_hi:[1,0] neg_lo:[0,1] neg_hi:[0,1]
	v_add_f32_e32 v11, v90, v11
	v_pk_mul_f32 v[62:63], v[30:31], v[30:31]
	v_add_f32_e32 v11, v91, v11
	v_add_f32_e32 v11, v62, v11
	v_add_f32_e32 v11, v63, v11
	v_mov_b32_e32 v13, v129
	v_lshl_add_u64 v[88:89], v[68:69], 0, v[12:13]
	v_pk_add_f32 v[28:29], v[64:65], v[66:67] op_sel_hi:[1,0] neg_lo:[0,1] neg_hi:[0,1]
	v_pk_mul_f32 v[64:65], v[28:29], v[28:29]
	v_lshl_add_u64 v[26:27], v[68:69], 0, v[14:15]
	v_add_f32_e32 v11, v64, v11
	v_add_f32_e32 v11, v65, v11
	s_waitcnt lgkmcnt(0)
	s_nop 1
	v_add_f32_dpp v11, v11, v11 quad_perm:[1,0,3,2] row_mask:0xf bank_mask:0xf
	s_nop 1
	v_add_f32_dpp v11, v11, v11 quad_perm:[2,3,0,1] row_mask:0xf bank_mask:0xf
	s_nop 1
	v_add_f32_dpp v11, v11, v11 row_half_mirror row_mask:0xf bank_mask:0xf
	s_nop 1
	v_add_f32_dpp v11, v11, v11 row_mirror row_mask:0xf bank_mask:0xf
	s_nop 1
	v_mov_b32_e32 v13, v11
	v_mov_b32_e32 v250, v11
	s_nop 1
	v_permlane16_swap_b32 v13, v250
	s_nop 1
	v_add_f32_e32 v11, v13, v250
	v_mov_b32_e32 v13, v11
	v_mov_b32_e32 v250, v11
	s_nop 1
	v_permlane32_swap_b32 v13, v250
	s_nop 1
	v_add_f32_e32 v11, v13, v250
	v_fmamk_f32 v11, v11, 0x3a800000, v182
	v_cmp_gt_f32_e32 vcc, s13, v11
	v_mul_f32_e32 v13, 0x4b800000, v11
	s_nop 0
	v_cndmask_b32_e32 v11, v11, v13, vcc
	v_rsq_f32_e32 v11, v11
	s_nop 0
	v_mul_f32_e32 v13, 0x45800000, v11
	v_cndmask_b32_e32 v62, v11, v13, vcc
	s_waitcnt vmcnt(4)
	v_pk_mul_f32 v[168:169], v[54:55], v[62:63] op_sel_hi:[1,0]
	v_pk_mul_f32 v[170:171], v[32:33], v[62:63] op_sel_hi:[1,0]
	v_add_co_u32_e32 v32, vcc, s25, v78
	s_nop 1
	v_addc_co_u32_e32 v33, vcc, 0, v79, vcc
	v_add_co_u32_e32 v50, vcc, s3, v78
	s_nop 1
	v_addc_co_u32_e32 v51, vcc, 0, v79, vcc
	v_pk_add_f32 v[172:173], v[152:153], 1.0 op_sel_hi:[1,0]
	v_pk_add_f32 v[174:175], v[154:155], 1.0 op_sel_hi:[1,0]
	v_pk_fma_f32 v[168:169], v[96:97], v[168:169], v[112:113]
	v_pk_fma_f32 v[170:171], v[98:99], v[170:171], v[114:115]
	s_nop 0
	v_pk_fma_f32 v[192:193], v[172:173], v[168:169], v[136:137]
	v_pk_fma_f32 v[194:195], v[174:175], v[170:171], v[138:139]
	v_cvt_pk_bf16_f32 v196, v168, v169
	v_cvt_pk_bf16_f32 v197, v170, v171
	v_cvt_pk_bf16_f32 v198, v192, v193
	v_cvt_pk_bf16_f32 v199, v194, v195
	global_store_dwordx2 v[32:33], v[196:197], off nt
	global_store_dwordx2 v[50:51], v[198:199], off nt
	v_pk_mul_f32 v[168:169], v[56:57], v[62:63] op_sel_hi:[1,0]
	v_pk_mul_f32 v[170:171], v[82:83], v[62:63] op_sel_hi:[1,0]
	v_pk_add_f32 v[172:173], v[156:157], 1.0 op_sel_hi:[1,0]
	v_pk_add_f32 v[174:175], v[158:159], 1.0 op_sel_hi:[1,0]
	v_pk_fma_f32 v[168:169], v[100:101], v[168:169], v[116:117]
	v_pk_fma_f32 v[170:171], v[102:103], v[170:171], v[118:119]
	s_nop 0
	v_pk_fma_f32 v[192:193], v[172:173], v[168:169], v[140:141]
	v_pk_fma_f32 v[194:195], v[174:175], v[170:171], v[142:143]
	v_cvt_pk_bf16_f32 v200, v168, v169
	v_cvt_pk_bf16_f32 v201, v170, v171
	v_cvt_pk_bf16_f32 v202, v192, v193
	v_cvt_pk_bf16_f32 v203, v194, v195
	global_store_dwordx2 v[32:33], v[200:201], off offset:512 nt
	global_store_dwordx2 v[50:51], v[202:203], off offset:512 nt
	v_pk_mul_f32 v[168:169], v[58:59], v[62:63] op_sel_hi:[1,0]
	v_pk_mul_f32 v[170:171], v[60:61], v[62:63] op_sel_hi:[1,0]
	v_pk_add_f32 v[172:173], v[160:161], 1.0 op_sel_hi:[1,0]
	v_pk_add_f32 v[174:175], v[162:163], 1.0 op_sel_hi:[1,0]
	v_pk_fma_f32 v[168:169], v[104:105], v[168:169], v[120:121]
	v_pk_fma_f32 v[170:171], v[106:107], v[170:171], v[122:123]
	s_nop 0
	v_pk_fma_f32 v[192:193], v[172:173], v[168:169], v[144:145]
	v_pk_fma_f32 v[194:195], v[174:175], v[170:171], v[146:147]
	v_cvt_pk_bf16_f32 v204, v168, v169
	v_cvt_pk_bf16_f32 v205, v170, v171
	v_cvt_pk_bf16_f32 v206, v192, v193
	v_cvt_pk_bf16_f32 v207, v194, v195
	global_store_dwordx2 v[32:33], v[204:205], off offset:1024 nt
	global_store_dwordx2 v[50:51], v[206:207], off offset:1024 nt
	v_pk_mul_f32 v[168:169], v[30:31], v[62:63] op_sel_hi:[1,0]
	v_pk_mul_f32 v[170:171], v[28:29], v[62:63] op_sel_hi:[1,0]
	v_pk_add_f32 v[172:173], v[164:165], 1.0 op_sel_hi:[1,0]
	v_pk_add_f32 v[174:175], v[166:167], 1.0 op_sel_hi:[1,0]
	v_pk_fma_f32 v[168:169], v[108:109], v[168:169], v[124:125]
	v_pk_fma_f32 v[170:171], v[110:111], v[170:171], v[126:127]
	s_nop 0
	v_pk_fma_f32 v[192:193], v[172:173], v[168:169], v[148:149]
	v_pk_fma_f32 v[194:195], v[174:175], v[170:171], v[150:151]
	v_cvt_pk_bf16_f32 v208, v168, v169
	v_cvt_pk_bf16_f32 v209, v170, v171
	v_cvt_pk_bf16_f32 v210, v192, v193
	v_cvt_pk_bf16_f32 v211, v194, v195
	global_store_dwordx2 v[32:33], v[208:209], off offset:1536 nt
	global_store_dwordx2 v[50:51], v[210:211], off offset:1536 nt
	v_cmp_lt_i32_e32 vcc, s22, v40
	v_add_u32_e32 v216, 0xffffe000, v40
	v_lshrrev_b32_e32 v216, 12, v216
	v_add_u32_e32 v216, 1, v216
	s_nop 0
	v_cndmask_b32_e32 v216, 0, v216, vcc
	v_mov_b64_e32 v[212:213], s[48:49]
	v_mad_u64_u32 v[212:213], s[38:39], v216, s23, v[212:213]
	s_mov_b64 s[38:39], 0x1000
	v_lshl_add_u64 v[212:213], v[212:213], 0, v[128:129]
	v_lshl_add_u64 v[214:215], v[212:213], 0, s[38:39]
	global_load_dwordx4 v[96:99], v[2:3], off
	global_load_dwordx4 v[112:115], v[4:5], off
	global_load_dwordx4 v[136:139], v[212:213], off
	global_load_dwordx4 v[152:155], v[214:215], off
	global_load_dwordx4 v[100:103], v[2:3], off offset:1024
	global_load_dwordx4 v[116:119], v[4:5], off offset:1024
	global_load_dwordx4 v[140:143], v[212:213], off offset:1024
	global_load_dwordx4 v[156:159], v[214:215], off offset:1024
	global_load_dwordx4 v[104:107], v[2:3], off offset:2048
	global_load_dwordx4 v[120:123], v[4:5], off offset:2048
	global_load_dwordx4 v[144:147], v[212:213], off offset:2048
	global_load_dwordx4 v[160:163], v[214:215], off offset:2048
	global_load_dwordx4 v[108:111], v[2:3], off offset:3072
	global_load_dwordx4 v[124:127], v[4:5], off offset:3072
	global_load_dwordx4 v[148:151], v[212:213], off offset:3072
	global_load_dwordx4 v[164:167], v[214:215], off offset:3072
	s_waitcnt vmcnt(24)
	v_mov_b32_e32 v24, v40
	v_mov_b32_e32 v32, v18
	v_mov_b32_e32 v33, v19
	v_mov_b32_e32 v30, v20
	v_mov_b32_e32 v31, v21
	v_mov_b32_e32 v28, v22
	v_mov_b32_e32 v29, v23
	v_mov_b32_e32 v26, v16
	v_mov_b32_e32 v27, v17
	s_andn2_b64 exec, exec, s[50:51]
	s_cbranch_execz .LBB0_933

.Lln1_nomod:
	v_lshlrev_b32_e32 v44, 16, v36
	v_and_b32_e32 v45, 0xffff0000, v36
	v_add_f32_e32 v1, 0, v44
	v_lshlrev_b32_e32 v46, 16, v37
	v_add_f32_e32 v1, v1, v45
	v_and_b32_e32 v47, 0xffff0000, v37
	v_add_f32_e32 v1, v1, v46
	v_lshlrev_b32_e32 v36, 16, v34
	v_add_f32_e32 v1, v1, v47
	v_and_b32_e32 v37, 0xffff0000, v34
	v_add_f32_e32 v1, v1, v36
	v_lshlrev_b32_e32 v34, 16, v35
	v_add_f32_e32 v1, v1, v37
	v_and_b32_e32 v35, 0xffff0000, v35
	v_add_f32_e32 v1, v1, v34
	v_lshlrev_b32_e32 v38, 16, v32
	v_add_f32_e32 v1, v1, v35
	v_and_b32_e32 v39, 0xffff0000, v32
	v_add_f32_e32 v1, v1, v38
	v_lshlrev_b32_e32 v32, 16, v33
	v_add_f32_e32 v1, v1, v39
	v_and_b32_e32 v33, 0xffff0000, v33
	v_add_f32_e32 v1, v1, v32
	v_lshlrev_b32_e32 v58, 16, v2
	v_add_f32_e32 v1, v1, v33
	v_and_b32_e32 v59, 0xffff0000, v2
	v_add_f32_e32 v1, v1, v58
	v_lshlrev_b32_e32 v2, 16, v3
	v_add_f32_e32 v1, v1, v59
	v_and_b32_e32 v3, 0xffff0000, v3
	v_add_f32_e32 v1, v1, v2
	v_add_f32_e32 v1, v1, v3
	v_cmp_lt_i32_e32 vcc, s22, v0
	s_mov_b64 s[44:45], -1
	v_lshlrev_b32_e32 v128, 2, v4
	s_waitcnt lgkmcnt(0)
	s_nop 1
	v_add_f32_dpp v1, v1, v1 quad_perm:[1,0,3,2] row_mask:0xf bank_mask:0xf
	s_nop 1
	v_add_f32_dpp v1, v1, v1 quad_perm:[2,3,0,1] row_mask:0xf bank_mask:0xf
	s_nop 1
	v_add_f32_dpp v1, v1, v1 row_half_mirror row_mask:0xf bank_mask:0xf
	s_nop 1
	v_add_f32_dpp v1, v1, v1 row_mirror row_mask:0xf bank_mask:0xf
	s_nop 1
	v_mov_b32_e32 v19, v1
	v_mov_b32_e32 v250, v1
	s_nop 1
	v_permlane16_swap_b32 v19, v250
	s_nop 1
	v_add_f32_e32 v1, v19, v250
	v_mov_b32_e32 v19, v1
	v_mov_b32_e32 v250, v1
	s_nop 1
	v_permlane32_swap_b32 v19, v250
	s_nop 1
	v_add_f32_e32 v1, v19, v250
	v_mul_f32_e32 v62, 0x3a800000, v1
	v_add_u32_e32 v1, 0xffffe000, v0
	v_lshrrev_b32_e32 v1, 12, v1
	v_add_u32_e32 v1, 1, v1
	v_pk_add_f32 v[40:41], v[38:39], v[62:63] op_sel_hi:[1,0] neg_lo:[0,1] neg_hi:[0,1]
	v_pk_add_f32 v[38:39], v[2:3], v[62:63] op_sel_hi:[1,0] neg_lo:[0,1] neg_hi:[0,1]
	v_cndmask_b32_e32 v2, 0, v1, vcc
	v_mov_b64_e32 v[0:1], s[50:51]
	v_pk_add_f32 v[48:49], v[36:37], v[62:63] op_sel_hi:[1,0] neg_lo:[0,1] neg_hi:[0,1]
	v_pk_add_f32 v[50:51], v[34:35], v[62:63] op_sel_hi:[1,0] neg_lo:[0,1] neg_hi:[0,1]
	v_pk_add_f32 v[36:37], v[58:59], v[62:63] op_sel_hi:[1,0] neg_lo:[0,1] neg_hi:[0,1]
	v_mad_u64_u32 v[34:35], s[2:3], v2, s23, v[0:1]
	v_pk_add_f32 v[44:45], v[44:45], v[62:63] op_sel_hi:[1,0] neg_lo:[0,1] neg_hi:[0,1]
	v_pk_add_f32 v[42:43], v[32:33], v[62:63] op_sel_hi:[1,0] neg_lo:[0,1] neg_hi:[0,1]
	v_pk_add_f32 v[76:77], v[46:47], v[62:63] op_sel_hi:[1,0] neg_lo:[0,1] neg_hi:[0,1]
	v_pk_mul_f32 v[62:63], v[44:45], v[44:45]
	v_pk_mul_f32 v[46:47], v[76:77], v[76:77]
	v_add_f32_e32 v19, v62, v63
	v_add_f32_e32 v19, v46, v19
	v_pk_mul_f32 v[64:65], v[48:49], v[48:49]
	v_add_f32_e32 v19, v47, v19
	v_add_f32_e32 v19, v64, v19
	v_pk_mul_f32 v[66:67], v[50:51], v[50:51]
	v_add_f32_e32 v19, v65, v19
	v_add_f32_e32 v19, v66, v19
	v_pk_mul_f32 v[68:69], v[40:41], v[40:41]
	v_add_f32_e32 v19, v67, v19
	v_add_f32_e32 v19, v68, v19
	v_pk_mul_f32 v[70:71], v[42:43], v[42:43]
	v_add_f32_e32 v19, v69, v19
	v_add_f32_e32 v19, v70, v19
	v_pk_mul_f32 v[72:73], v[36:37], v[36:37]
	v_add_f32_e32 v19, v71, v19
	v_add_f32_e32 v19, v72, v19
	v_pk_mul_f32 v[74:75], v[38:39], v[38:39]
	v_add_f32_e32 v19, v73, v19
	v_add_f32_e32 v19, v74, v19
	v_add_f32_e32 v19, v75, v19
	s_mov_b64 s[2:3], 0x1000
	v_lshl_add_u64 v[32:33], v[34:35], 0, s[2:3]
	s_waitcnt lgkmcnt(0)
	s_nop 1
	v_add_f32_dpp v19, v19, v19 quad_perm:[1,0,3,2] row_mask:0xf bank_mask:0xf
	s_nop 1
	v_add_f32_dpp v19, v19, v19 quad_perm:[2,3,0,1] row_mask:0xf bank_mask:0xf
	s_nop 1
	v_add_f32_dpp v19, v19, v19 row_half_mirror row_mask:0xf bank_mask:0xf
	s_nop 1
	v_add_f32_dpp v19, v19, v19 row_mirror row_mask:0xf bank_mask:0xf
	s_nop 1
	v_mov_b32_e32 v21, v19
	v_mov_b32_e32 v250, v19
	s_nop 1
	v_permlane16_swap_b32 v21, v250
	s_nop 1
	v_add_f32_e32 v19, v21, v250
	v_mov_b32_e32 v21, v19
	v_mov_b32_e32 v250, v19
	s_nop 1
	v_permlane32_swap_b32 v21, v250
	s_nop 1
	v_add_f32_e32 v19, v21, v250
	v_fmamk_f32 v19, v19, 0x3a800000, v182
	v_cmp_gt_f32_e32 vcc, s13, v19
	v_mul_f32_e32 v21, 0x4b800000, v19
	s_nop 0
	v_cndmask_b32_e32 v19, v19, v21, vcc
	v_rsq_f32_e32 v19, v19
	s_nop 0
	v_mul_f32_e32 v21, 0x45800000, v19
	v_cndmask_b32_e32 v46, v19, v21, vcc
	s_waitcnt vmcnt(0)
	v_lshl_add_u64 v[74:75], v[14:15], 0, v[10:11]
	s_and_b64 vcc, exec, s[48:49]
	s_cbranch_vccz .Lln1_last
	v_add_co_u32_e32 v0, vcc, s25, v74
	s_nop 1
	v_addc_co_u32_e32 v1, vcc, 0, v75, vcc
	v_add_co_u32_e32 v2, vcc, 0x1d600000, v74
	s_nop 1
	v_addc_co_u32_e32 v3, vcc, 0, v75, vcc
	v_pk_mul_f32 v[58:59], v[44:45], v[46:47] op_sel_hi:[1,0]
	v_pk_mul_f32 v[60:61], v[76:77], v[46:47] op_sel_hi:[1,0]
	v_pk_add_f32 v[62:63], v[208:209], 1.0 op_sel_hi:[1,0]
	v_pk_add_f32 v[64:65], v[210:211], 1.0 op_sel_hi:[1,0]
	v_pk_fma_f32 v[58:59], v[134:135], v[58:59], v[150:151]
	v_pk_fma_f32 v[60:61], v[136:137], v[60:61], v[152:153]
	s_nop 0
	v_pk_fma_f32 v[66:67], v[58:59], v[62:63], v[192:193]
	v_pk_fma_f32 v[68:69], v[60:61], v[64:65], v[194:195]
	v_cvt_pk_bf16_f32 v70, v58, v59
	v_cvt_pk_bf16_f32 v71, v60, v61
	v_cvt_pk_bf16_f32 v72, v66, v67
	v_cvt_pk_bf16_f32 v73, v68, v69
	global_store_dwordx2 v[0:1], v[70:71], off nt
	global_store_dwordx2 v[2:3], v[72:73], off nt
	v_pk_mul_f32 v[58:59], v[48:49], v[46:47] op_sel_hi:[1,0]
	v_pk_mul_f32 v[60:61], v[50:51], v[46:47] op_sel_hi:[1,0]
	v_pk_add_f32 v[62:63], v[212:213], 1.0 op_sel_hi:[1,0]
	v_pk_add_f32 v[64:65], v[214:215], 1.0 op_sel_hi:[1,0]
	v_pk_fma_f32 v[58:59], v[138:139], v[58:59], v[154:155]
	v_pk_fma_f32 v[60:61], v[140:141], v[60:61], v[156:157]
	s_nop 0
	v_pk_fma_f32 v[66:67], v[58:59], v[62:63], v[196:197]
	v_pk_fma_f32 v[68:69], v[60:61], v[64:65], v[198:199]
	v_cvt_pk_bf16_f32 v32, v58, v59
	v_cvt_pk_bf16_f32 v33, v60, v61
	v_cvt_pk_bf16_f32 v34, v66, v67
	v_cvt_pk_bf16_f32 v35, v68, v69
	global_store_dwordx2 v[0:1], v[32:33], off offset:512 nt
	global_store_dwordx2 v[2:3], v[34:35], off offset:512 nt
	v_pk_mul_f32 v[58:59], v[40:41], v[46:47] op_sel_hi:[1,0]
	v_pk_mul_f32 v[60:61], v[42:43], v[46:47] op_sel_hi:[1,0]
	v_pk_add_f32 v[62:63], v[216:217], 1.0 op_sel_hi:[1,0]
	v_pk_add_f32 v[64:65], v[218:219], 1.0 op_sel_hi:[1,0]
	v_pk_fma_f32 v[58:59], v[142:143], v[58:59], v[158:159]
	v_pk_fma_f32 v[60:61], v[144:145], v[60:61], v[160:161]
	s_nop 0
	v_pk_fma_f32 v[66:67], v[58:59], v[62:63], v[200:201]
	v_pk_fma_f32 v[68:69], v[60:61], v[64:65], v[202:203]
	v_cvt_pk_bf16_f32 v70, v58, v59
	v_cvt_pk_bf16_f32 v71, v60, v61
	v_cvt_pk_bf16_f32 v72, v66, v67
	v_cvt_pk_bf16_f32 v73, v68, v69
	global_store_dwordx2 v[0:1], v[70:71], off offset:1024 nt
	global_store_dwordx2 v[2:3], v[72:73], off offset:1024 nt
	v_pk_mul_f32 v[58:59], v[36:37], v[46:47] op_sel_hi:[1,0]
	v_pk_mul_f32 v[60:61], v[38:39], v[46:47] op_sel_hi:[1,0]
	v_pk_add_f32 v[62:63], v[220:221], 1.0 op_sel_hi:[1,0]
	v_pk_add_f32 v[64:65], v[222:223], 1.0 op_sel_hi:[1,0]
	v_pk_fma_f32 v[58:59], v[146:147], v[58:59], v[162:163]
	v_pk_fma_f32 v[60:61], v[148:149], v[60:61], v[164:165]
	s_nop 0
	v_pk_fma_f32 v[66:67], v[58:59], v[62:63], v[204:205]
	v_pk_fma_f32 v[68:69], v[60:61], v[64:65], v[206:207]
	v_cvt_pk_bf16_f32 v32, v58, v59
	v_cvt_pk_bf16_f32 v33, v60, v61
	v_cvt_pk_bf16_f32 v34, v66, v67
	v_cvt_pk_bf16_f32 v35, v68, v69
	global_store_dwordx2 v[0:1], v[32:33], off offset:1536 nt
	global_store_dwordx2 v[2:3], v[34:35], off offset:1536 nt
	s_branch .LBB0_1129
.Lln1_last:
	v_pk_mul_f32 v[58:59], v[44:45], v[46:47] op_sel_hi:[1,0]
	v_pk_mul_f32 v[60:61], v[76:77], v[46:47] op_sel_hi:[1,0]
	v_pk_fma_f32 v[58:59], v[134:135], v[58:59], v[150:151]
	v_pk_fma_f32 v[60:61], v[136:137], v[60:61], v[152:153]
	s_nop 0
	global_store_dwordx4 v[16:17], v[58:61], off offset:-2048 nt
	v_pk_mul_f32 v[62:63], v[48:49], v[46:47] op_sel_hi:[1,0]
	v_pk_mul_f32 v[64:65], v[50:51], v[46:47] op_sel_hi:[1,0]
	v_pk_fma_f32 v[62:63], v[138:139], v[62:63], v[154:155]
	v_pk_fma_f32 v[64:65], v[140:141], v[64:65], v[156:157]
	s_nop 0
	global_store_dwordx4 v[16:17], v[62:65], off offset:-1024 nt
	v_pk_mul_f32 v[58:59], v[40:41], v[46:47] op_sel_hi:[1,0]
	v_pk_mul_f32 v[60:61], v[42:43], v[46:47] op_sel_hi:[1,0]
	v_pk_fma_f32 v[58:59], v[142:143], v[58:59], v[158:159]
	v_pk_fma_f32 v[60:61], v[144:145], v[60:61], v[160:161]
	s_nop 0
	global_store_dwordx4 v[16:17], v[58:61], off nt
	v_pk_mul_f32 v[62:63], v[36:37], v[46:47] op_sel_hi:[1,0]
	v_pk_mul_f32 v[64:65], v[38:39], v[46:47] op_sel_hi:[1,0]
	v_pk_fma_f32 v[62:63], v[146:147], v[62:63], v[162:163]
	v_pk_fma_f32 v[64:65], v[148:149], v[64:65], v[164:165]
	s_nop 0
	global_store_dwordx4 v[16:17], v[62:65], off offset:1024 nt
	s_branch .LBB0_1129
